# grid barrier: followers poll the global generation word directly (skip the per-XCC release hop), on top of early acquire + combine hoist
# speedup vs baseline: 1.0251x; 1.0000x over previous
; __device__ __forceinline__ unsigned xb_ld(unsigned* p)              { return __hip_atomic_load(p, __ATOMIC_RELAXED, __HIP_MEMORY_SCOPE_AGENT); }
; __device__ __forceinline__ unsigned xb_add(unsigned* p, unsigned v) { return __hip_atomic_fetch_add(p, v, __ATOMIC_RELAXED, __HIP_MEMORY_SCOPE_AGENT); }
; #define XB_SPIN(cond, bar) do { unsigned _sp = 0; while (cond) { __builtin_amdgcn_s_sleep(1); \
;     if ((++_sp & 255u) == 0u) { if (xb_ld(&(bar)[XB_TMO])) break; if (_sp > XB_SPIN_CAP) { atomicAdd(&(bar)[XB_TMO], 1u); break; } } } } while (0)
; __device__ __forceinline__ void xcd_barrier(const XcdBarrier& b) {
;     ...
;         const unsigned old = xb_add(&bar[XB_XSUB(b.x)], 1u);
;         const unsigned gen = old / nloc;
;         if (old + 1u == (gen + 1u) * nloc) {
;             __builtin_amdgcn_fence(__ATOMIC_RELEASE, "agent");
;             asm volatile("s_waitcnt vmcnt(0)" ::: "memory");
;             const unsigned og = xb_add(&bar[XB_TOP], 1u);
;             const unsigned tg = og / nx;
;             if (og + 1u == (tg + 1u) * nx) xb_add(&bar[XB_TOPGEN], 1u);
;             else XB_SPIN(xb_ld(&bar[XB_TOPGEN]) == tg, bar);
;             __builtin_amdgcn_fence(__ATOMIC_ACQUIRE, "agent");
;             xb_add(&bar[XB_XGEN(b.x)], 1u);
;             asm volatile("s_waitcnt vmcnt(0)" ::: "memory");
;         } else {
;             XB_SPIN(xb_ld(&bar[XB_XGEN(b.x)]) == gen, bar);
.LBB0_225:
	s_or_b64 exec, exec, s[42:43]
	v_cvt_f32_u32_e32 v5, v3
	s_waitcnt vmcnt(0)
	v_readfirstlane_b32 s3, v4
	v_sub_u32_e32 v4, 0, v3
	v_rcp_iflag_f32_e32 v5, v5
	v_add_u32_e32 v6, s3, v0
	v_mul_f32_e32 v5, 0x4f7ffffe, v5
	v_cvt_u32_f32_e32 v5, v5
	v_mul_lo_u32 v0, v4, v5
	v_mul_hi_u32 v0, v5, v0
	v_add_u32_e32 v0, v5, v0
	v_mul_hi_u32 v0, v6, v0
	v_mul_lo_u32 v4, v0, v3
	v_sub_u32_e32 v4, v6, v4
	v_add_u32_e32 v5, 1, v0
	v_cmp_ge_u32_e32 vcc, v4, v3
	s_nop 1
	v_cndmask_b32_e32 v0, v0, v5, vcc
	v_sub_u32_e32 v5, v4, v3
	v_cndmask_b32_e32 v4, v4, v5, vcc
	v_add_u32_e32 v5, 1, v0
	v_cmp_ge_u32_e32 vcc, v4, v3
	v_add_u32_e32 v4, 1, v6
	s_nop 0
	v_cndmask_b32_e32 v0, v0, v5, vcc
	v_mul_lo_u32 v5, v3, v0
	v_add_u32_e32 v3, v5, v3
	v_cmp_ne_u32_e32 vcc, v4, v3
	s_and_saveexec_b64 s[12:13], vcc
	s_xor_b64 s[42:43], exec, s[12:13]
	s_cbranch_execz .LBB0_239
	buffer_inv sc1
	v_readlane_b32 s12, v255, 14
	v_readlane_b32 s13, v255, 15
	s_waitcnt lgkmcnt(0)
	s_nop 3
	global_load_dword v2, v1, s[12:13] sc1
	s_waitcnt vmcnt(0)
	v_cmp_eq_u32_e32 vcc, v2, v0
	s_and_saveexec_b64 s[44:45], vcc
	s_cbranch_execz .LBB0_238
	s_mov_b32 s3, 1
	s_mov_b64 s[46:47], 0
	s_branch .LBB0_229

; __device__ __forceinline__ unsigned xb_ld(unsigned* p)              { return __hip_atomic_load(p, __ATOMIC_RELAXED, __HIP_MEMORY_SCOPE_AGENT); }
; __device__ __forceinline__ unsigned xb_add(unsigned* p, unsigned v) { return __hip_atomic_fetch_add(p, v, __ATOMIC_RELAXED, __HIP_MEMORY_SCOPE_AGENT); }
; #define XB_SPIN(cond, bar) do { unsigned _sp = 0; while (cond) { __builtin_amdgcn_s_sleep(1); \
;     if ((++_sp & 255u) == 0u) { if (xb_ld(&(bar)[XB_TMO])) break; if (_sp > XB_SPIN_CAP) { atomicAdd(&(bar)[XB_TMO], 1u); break; } } } } while (0)
; __device__ __forceinline__ void xcd_barrier(const XcdBarrier& b) {
;     ...
;         const unsigned old = xb_add(&bar[XB_XSUB(b.x)], 1u);
;         const unsigned gen = old / nloc;
;         if (old + 1u == (gen + 1u) * nloc) {
;             __builtin_amdgcn_fence(__ATOMIC_RELEASE, "agent");
;             asm volatile("s_waitcnt vmcnt(0)" ::: "memory");
;             const unsigned og = xb_add(&bar[XB_TOP], 1u);
;             const unsigned tg = og / nx;
;             if (og + 1u == (tg + 1u) * nx) xb_add(&bar[XB_TOPGEN], 1u);
;             else XB_SPIN(xb_ld(&bar[XB_TOPGEN]) == tg, bar);
;             __builtin_amdgcn_fence(__ATOMIC_ACQUIRE, "agent");
;             xb_add(&bar[XB_XGEN(b.x)], 1u);
;             asm volatile("s_waitcnt vmcnt(0)" ::: "memory");
;         } else {
;             XB_SPIN(xb_ld(&bar[XB_XGEN(b.x)]) == gen, bar);
.LBB0_302:
	s_or_b64 exec, exec, s[38:39]
	v_cvt_f32_u32_e32 v5, v3
	s_waitcnt vmcnt(0)
	v_readfirstlane_b32 s12, v4
	v_sub_u32_e32 v4, 0, v3
	v_rcp_iflag_f32_e32 v5, v5
	v_add_u32_e32 v6, s12, v0
	v_mul_f32_e32 v5, 0x4f7ffffe, v5
	v_cvt_u32_f32_e32 v5, v5
	v_mul_lo_u32 v0, v4, v5
	v_mul_hi_u32 v0, v5, v0
	v_add_u32_e32 v0, v5, v0
	v_mul_hi_u32 v0, v6, v0
	v_mul_lo_u32 v4, v0, v3
	v_sub_u32_e32 v4, v6, v4
	v_add_u32_e32 v5, 1, v0
	v_cmp_ge_u32_e32 vcc, v4, v3
	s_nop 1
	v_cndmask_b32_e32 v0, v0, v5, vcc
	v_sub_u32_e32 v5, v4, v3
	v_cndmask_b32_e32 v4, v4, v5, vcc
	v_add_u32_e32 v5, 1, v0
	v_cmp_ge_u32_e32 vcc, v4, v3
	v_add_u32_e32 v4, 1, v6
	s_nop 0
	v_cndmask_b32_e32 v0, v0, v5, vcc
	v_mul_lo_u32 v5, v3, v0
	v_add_u32_e32 v3, v5, v3
	v_cmp_ne_u32_e32 vcc, v4, v3
	s_and_saveexec_b64 s[12:13], vcc
	s_xor_b64 s[38:39], exec, s[12:13]
	s_cbranch_execz .LBB0_316
	buffer_inv sc1
	v_readlane_b32 s12, v255, 14
	v_readlane_b32 s13, v255, 15
	s_waitcnt lgkmcnt(0)
	s_nop 3
	global_load_dword v2, v1, s[12:13] sc1
	s_waitcnt vmcnt(0)
	v_cmp_eq_u32_e32 vcc, v2, v0
	s_and_saveexec_b64 s[40:41], vcc
	s_cbranch_execz .LBB0_315
	s_mov_b32 s12, 1
	s_mov_b64 s[42:43], 0
	s_branch .LBB0_306

; __device__ __forceinline__ unsigned xb_ld(unsigned* p)              { return __hip_atomic_load(p, __ATOMIC_RELAXED, __HIP_MEMORY_SCOPE_AGENT); }
; __device__ __forceinline__ unsigned xb_add(unsigned* p, unsigned v) { return __hip_atomic_fetch_add(p, v, __ATOMIC_RELAXED, __HIP_MEMORY_SCOPE_AGENT); }
; #define XB_SPIN(cond, bar) do { unsigned _sp = 0; while (cond) { __builtin_amdgcn_s_sleep(1); \
;     if ((++_sp & 255u) == 0u) { if (xb_ld(&(bar)[XB_TMO])) break; if (_sp > XB_SPIN_CAP) { atomicAdd(&(bar)[XB_TMO], 1u); break; } } } } while (0)
; __device__ __forceinline__ void xcd_barrier(const XcdBarrier& b) {
;     ...
;         const unsigned old = xb_add(&bar[XB_XSUB(b.x)], 1u);
;         const unsigned gen = old / nloc;
;         if (old + 1u == (gen + 1u) * nloc) {
;             __builtin_amdgcn_fence(__ATOMIC_RELEASE, "agent");
;             asm volatile("s_waitcnt vmcnt(0)" ::: "memory");
;             const unsigned og = xb_add(&bar[XB_TOP], 1u);
;             const unsigned tg = og / nx;
;             if (og + 1u == (tg + 1u) * nx) xb_add(&bar[XB_TOPGEN], 1u);
;             else XB_SPIN(xb_ld(&bar[XB_TOPGEN]) == tg, bar);
;             __builtin_amdgcn_fence(__ATOMIC_ACQUIRE, "agent");
;             xb_add(&bar[XB_XGEN(b.x)], 1u);
;             asm volatile("s_waitcnt vmcnt(0)" ::: "memory");
;         } else {
;             XB_SPIN(xb_ld(&bar[XB_XGEN(b.x)]) == gen, bar);
.LBB0_476:
	s_or_b64 exec, exec, s[38:39]
	v_cvt_f32_u32_e32 v5, v3
	s_waitcnt vmcnt(0)
	v_readfirstlane_b32 s3, v4
	v_sub_u32_e32 v4, 0, v3
	v_rcp_iflag_f32_e32 v5, v5
	v_add_u32_e32 v6, s3, v0
	v_mul_f32_e32 v5, 0x4f7ffffe, v5
	v_cvt_u32_f32_e32 v5, v5
	v_mul_lo_u32 v0, v4, v5
	v_mul_hi_u32 v0, v5, v0
	v_add_u32_e32 v0, v5, v0
	v_mul_hi_u32 v0, v6, v0
	v_mul_lo_u32 v4, v0, v3
	v_sub_u32_e32 v4, v6, v4
	v_add_u32_e32 v5, 1, v0
	v_cmp_ge_u32_e32 vcc, v4, v3
	s_nop 1
	v_cndmask_b32_e32 v0, v0, v5, vcc
	v_sub_u32_e32 v5, v4, v3
	v_cndmask_b32_e32 v4, v4, v5, vcc
	v_add_u32_e32 v5, 1, v0
	v_cmp_ge_u32_e32 vcc, v4, v3
	v_add_u32_e32 v4, 1, v6
	s_nop 0
	v_cndmask_b32_e32 v0, v0, v5, vcc
	v_mul_lo_u32 v5, v3, v0
	v_add_u32_e32 v3, v5, v3
	v_cmp_ne_u32_e32 vcc, v4, v3
	s_and_saveexec_b64 s[12:13], vcc
	s_xor_b64 s[38:39], exec, s[12:13]
	s_cbranch_execz .LBB0_490
	buffer_inv sc1
	v_readlane_b32 s12, v255, 14
	v_readlane_b32 s13, v255, 15
	s_waitcnt lgkmcnt(0)
	s_nop 3
	global_load_dword v2, v1, s[12:13] sc1
	s_waitcnt vmcnt(0)
	v_cmp_eq_u32_e32 vcc, v2, v0
	s_and_saveexec_b64 s[40:41], vcc
	s_cbranch_execz .LBB0_489
	s_mov_b32 s3, 1
	s_mov_b64 s[42:43], 0
	s_branch .LBB0_480

; __device__ __forceinline__ unsigned xb_ld(unsigned* p)              { return __hip_atomic_load(p, __ATOMIC_RELAXED, __HIP_MEMORY_SCOPE_AGENT); }
; __device__ __forceinline__ unsigned xb_add(unsigned* p, unsigned v) { return __hip_atomic_fetch_add(p, v, __ATOMIC_RELAXED, __HIP_MEMORY_SCOPE_AGENT); }
; #define XB_SPIN(cond, bar) do { unsigned _sp = 0; while (cond) { __builtin_amdgcn_s_sleep(1); \
;     if ((++_sp & 255u) == 0u) { if (xb_ld(&(bar)[XB_TMO])) break; if (_sp > XB_SPIN_CAP) { atomicAdd(&(bar)[XB_TMO], 1u); break; } } } } while (0)
; __device__ __forceinline__ void xcd_barrier(const XcdBarrier& b) {
;     ...
;         const unsigned old = xb_add(&bar[XB_XSUB(b.x)], 1u);
;         const unsigned gen = old / nloc;
;         if (old + 1u == (gen + 1u) * nloc) {
;             __builtin_amdgcn_fence(__ATOMIC_RELEASE, "agent");
;             asm volatile("s_waitcnt vmcnt(0)" ::: "memory");
;             const unsigned og = xb_add(&bar[XB_TOP], 1u);
;             const unsigned tg = og / nx;
;             if (og + 1u == (tg + 1u) * nx) xb_add(&bar[XB_TOPGEN], 1u);
;             else XB_SPIN(xb_ld(&bar[XB_TOPGEN]) == tg, bar);
;             __builtin_amdgcn_fence(__ATOMIC_ACQUIRE, "agent");
;             xb_add(&bar[XB_XGEN(b.x)], 1u);
;             asm volatile("s_waitcnt vmcnt(0)" ::: "memory");
;         } else {
;             XB_SPIN(xb_ld(&bar[XB_XGEN(b.x)]) == gen, bar);
.LBB0_621:
	s_or_b64 exec, exec, s[38:39]
	v_cvt_f32_u32_e32 v5, v3
	s_waitcnt vmcnt(0)
	v_readfirstlane_b32 s6, v4
	v_sub_u32_e32 v4, 0, v3
	v_rcp_iflag_f32_e32 v5, v5
	v_add_u32_e32 v6, s6, v0
	v_mul_f32_e32 v5, 0x4f7ffffe, v5
	v_cvt_u32_f32_e32 v5, v5
	v_mul_lo_u32 v0, v4, v5
	v_mul_hi_u32 v0, v5, v0
	v_add_u32_e32 v0, v5, v0
	v_mul_hi_u32 v0, v6, v0
	v_mul_lo_u32 v4, v0, v3
	v_sub_u32_e32 v4, v6, v4
	v_add_u32_e32 v5, 1, v0
	v_cmp_ge_u32_e32 vcc, v4, v3
	s_nop 1
	v_cndmask_b32_e32 v0, v0, v5, vcc
	v_sub_u32_e32 v5, v4, v3
	v_cndmask_b32_e32 v4, v4, v5, vcc
	v_add_u32_e32 v5, 1, v0
	v_cmp_ge_u32_e32 vcc, v4, v3
	v_add_u32_e32 v4, 1, v6
	s_nop 0
	v_cndmask_b32_e32 v0, v0, v5, vcc
	v_mul_lo_u32 v5, v3, v0
	v_add_u32_e32 v3, v5, v3
	v_cmp_ne_u32_e32 vcc, v4, v3
	s_and_saveexec_b64 s[12:13], vcc
	s_xor_b64 s[38:39], exec, s[12:13]
	s_cbranch_execz .LBB0_635
	buffer_inv sc1
	v_readlane_b32 s12, v255, 14
	v_readlane_b32 s13, v255, 15
	s_waitcnt lgkmcnt(0)
	s_nop 3
	global_load_dword v2, v1, s[12:13] sc1
	s_waitcnt vmcnt(0)
	v_cmp_eq_u32_e32 vcc, v2, v0
	s_and_saveexec_b64 s[40:41], vcc
	s_cbranch_execz .LBB0_634
	s_mov_b32 s9, 1
	s_mov_b64 s[42:43], 0
	s_branch .LBB0_625
